# S5 tail computes Y^T (Cm^T*H^T) so each lane holds 4 contiguous channels: 2 dwordx4 stores per chunk instead of 8 dword stores
# speedup vs baseline: 1.0378x; 1.0031x over previous
.LBB0_100:
	s_waitcnt vmcnt(0)
	v_readfirstlane_b32 s52, v149
	s_mov_b32 s50, 0x10000
	s_mov_b32 s51, 0
	s_mov_b32 s54, 0x1000
	s_mov_b32 s55, 0
	s_mov_b32 s56, 0x3000
	s_mov_b32 s57, 0
	v_add_u32_e32 v0, 32, v210
	v_cndmask_b32_e64 v0, v0, 0, s[40:41]
	v_and_or_b32 v12, v203, 15, v0
	v_ashrrev_i32_e32 v13, 31, v12
	v_cvt_pk_bf16_f32 v212, v8, v9
	v_cvt_pk_bf16_f32 v213, v10, v11
	v_cvt_pk_bf16_f32 v214, v4, v5
	v_cvt_pk_bf16_f32 v215, v6, v7
	v_and_b32_e32 v16, 48, v203
	v_and_b32_e32 v17, 15, v203
	v_mfma_f32_32x32x16_bf16 v[34:49], v[212:215], v[66:69], 0
	v_mfma_f32_32x32x16_bf16 v[50:65], v[212:215], v[74:77], 0
	v_lshlrev_b32_e32 v17, 2, v17
	v_sub_u32_e32 v16, v16, v17
	v_ashrrev_i32_e32 v17, 31, v16
	v_lshl_add_u64 v[14:15], v[12:13], 0, v[164:165]
	v_lshlrev_b64 v[14:15], 12, v[14:15]
	v_lshl_add_u64 v[14:15], v[162:163], 0, v[14:15]
	v_lshl_add_u64 v[240:241], v[14:15], 0, v[16:17]
	v_lshl_add_u64 v[14:15], v[12:13], 0, v[166:167]
	v_lshlrev_b64 v[14:15], 12, v[14:15]
	v_lshl_add_u64 v[14:15], v[162:163], 0, v[14:15]
	v_lshl_add_u64 v[244:245], v[14:15], 0, v[16:17]
	s_nop 7
	s_cmp_lg_u64 s[40:41], 0
	s_cbranch_scc1 .LS5P_loopd0
	s_mov_b32 s50, 0xffff0000
	s_mov_b32 s51, -1
.LS5P_loopd1:
	s_add_u32 s20, s28, 2
	s_cmp_lt_u32 s20, s52
	s_cselect_b64 s[58:59], s[50:51], 0
	v_lshl_add_u64 v[248:249], v[248:249], 0, s[58:59]
	global_load_dwordx4 v[110:113], v[248:249], off offset:16
	global_load_dwordx4 v[106:109], v[248:249], off
	ds_read_b128 v[216:219], v208
	ds_read_b128 v[220:223], v208 offset:4352
	ds_read_b128 v[224:227], v208 offset:64
	ds_read_b128 v[228:231], v208 offset:4416
	v_fmac_f32_e32 v49, v152, v182
	v_fmac_f32_e32 v65, v152, v178
	v_fma_f32 v49, -v153, v178, v49
	v_fmac_f32_e32 v65, v153, v182
	v_mfma_f32_32x32x16_bf16 v[2:17], v[212:215], v[70:73], 0
	v_fmac_f32_e32 v48, v152, v49
	v_fmac_f32_e32 v64, v152, v65
	v_cvt_pk_bf16_f32 v184, v49, v65
	v_fma_f32 v48, -v153, v65, v48
	v_fmac_f32_e32 v64, v153, v49
	ds_write_b32 v207, v184 offset:4080
	v_fmac_f32_e32 v47, v152, v48
	v_fmac_f32_e32 v63, v152, v64
	v_cvt_pk_bf16_f32 v185, v48, v64
	v_fma_f32 v47, -v153, v64, v47
	v_fmac_f32_e32 v63, v153, v48
	ds_write_b32 v207, v185 offset:3808
	v_mfma_f32_32x32x16_bf16 v[18:33], v[212:215], v[78:81], 0
	v_fmac_f32_e32 v46, v152, v47
	v_fmac_f32_e32 v62, v152, v63
	v_cvt_pk_bf16_f32 v184, v47, v63
	v_fma_f32 v46, -v153, v63, v46
	v_fmac_f32_e32 v62, v153, v47
	ds_write_b32 v207, v184 offset:3536
	v_fmac_f32_e32 v45, v152, v46
	v_fmac_f32_e32 v61, v152, v62
	v_cvt_pk_bf16_f32 v185, v46, v62
	v_fma_f32 v45, -v153, v62, v45
	v_fmac_f32_e32 v61, v153, v46
	ds_write_b32 v207, v185 offset:3264
	s_waitcnt lgkmcnt(6)
	v_mfma_f32_16x16x32_bf16 v[232:235], v[82:85], v[216:219], 0
	v_fmac_f32_e32 v44, v152, v45
	v_fmac_f32_e32 v60, v152, v61
	v_cvt_pk_bf16_f32 v184, v45, v61
	v_fma_f32 v44, -v153, v61, v44
	v_fmac_f32_e32 v60, v153, v45
	ds_write_b32 v207, v184 offset:2992
	v_mfma_f32_16x16x32_bf16 v[236:239], v[82:85], v[220:223], 0
	v_fmac_f32_e32 v43, v152, v44
	v_fmac_f32_e32 v59, v152, v60
	v_cvt_pk_bf16_f32 v185, v44, v60
	v_fma_f32 v43, -v153, v60, v43
	v_fmac_f32_e32 v59, v153, v44
	ds_write_b32 v207, v185 offset:2720
	s_waitcnt lgkmcnt(6)
	v_mfma_f32_16x16x32_bf16 v[232:235], v[86:89], v[224:227], v[232:235]
	v_fmac_f32_e32 v42, v152, v43
	v_fmac_f32_e32 v58, v152, v59
	v_cvt_pk_bf16_f32 v184, v43, v59
	v_fma_f32 v42, -v153, v59, v42
	v_fmac_f32_e32 v58, v153, v43
	ds_write_b32 v207, v184 offset:2448
	v_mfma_f32_16x16x32_bf16 v[236:239], v[86:89], v[228:231], v[236:239]
	v_fmac_f32_e32 v41, v152, v42
	v_fmac_f32_e32 v57, v152, v58
	v_cvt_pk_bf16_f32 v185, v42, v58
	v_fma_f32 v41, -v153, v58, v41
	v_fmac_f32_e32 v57, v153, v42
	ds_write_b32 v207, v185 offset:2176
	ds_read_b128 v[216:219], v208 offset:128
	ds_read_b128 v[220:223], v208 offset:4480
	ds_read_b128 v[224:227], v208 offset:192
	ds_read_b128 v[228:231], v208 offset:4544
	v_fmac_f32_e32 v40, v152, v41
	v_fmac_f32_e32 v56, v152, v57
	v_cvt_pk_bf16_f32 v184, v41, v57
	v_fma_f32 v40, -v153, v57, v40
	v_fmac_f32_e32 v56, v153, v41
	ds_write_b32 v207, v184 offset:1904
	v_fmac_f32_e32 v39, v152, v40
	v_fmac_f32_e32 v55, v152, v56
	v_cvt_pk_bf16_f32 v185, v40, v56
	v_fma_f32 v39, -v153, v56, v39
	v_fmac_f32_e32 v55, v153, v40
	ds_write_b32 v207, v185 offset:1632
	v_fmac_f32_e32 v38, v152, v39
	v_fmac_f32_e32 v54, v152, v55
	v_cvt_pk_bf16_f32 v184, v39, v55
	v_fma_f32 v38, -v153, v55, v38
	v_fmac_f32_e32 v54, v153, v39
	ds_write_b32 v207, v184 offset:1360
	s_waitcnt lgkmcnt(5)
	v_mfma_f32_16x16x32_bf16 v[232:235], v[90:93], v[216:219], v[232:235]
	v_fmac_f32_e32 v37, v152, v38
	v_fmac_f32_e32 v53, v152, v54
	v_cvt_pk_bf16_f32 v185, v38, v54
	v_fma_f32 v37, -v153, v54, v37
	v_fmac_f32_e32 v53, v153, v38
	ds_write_b32 v207, v185 offset:1088
	v_mfma_f32_16x16x32_bf16 v[236:239], v[90:93], v[220:223], v[236:239]
	v_fmac_f32_e32 v36, v152, v37
	v_fmac_f32_e32 v52, v152, v53
	v_cvt_pk_bf16_f32 v184, v37, v53
	v_fma_f32 v36, -v153, v53, v36
	v_fmac_f32_e32 v52, v153, v37
	ds_write_b32 v207, v184 offset:816
	s_waitcnt lgkmcnt(5)
	v_mfma_f32_16x16x32_bf16 v[232:235], v[94:97], v[224:227], v[232:235]
	v_fmac_f32_e32 v35, v152, v36
	v_fmac_f32_e32 v51, v152, v52
	v_cvt_pk_bf16_f32 v185, v36, v52
	v_fma_f32 v35, -v153, v52, v35
	v_fmac_f32_e32 v51, v153, v36
	ds_write_b32 v207, v185 offset:544
	v_mfma_f32_16x16x32_bf16 v[236:239], v[94:97], v[228:231], v[236:239]
	v_fma_f32 v182, v152, v35, v34
	v_fma_f32 v178, v152, v51, v50
	v_cvt_pk_bf16_f32 v184, v35, v51
	v_fma_f32 v182, -v153, v51, v182
	v_fmac_f32_e32 v178, v153, v35
	ds_write_b32 v207, v184 offset:272
	v_cvt_pk_bf16_f32 v185, v182, v178
	ds_write_b32 v207, v185 offset:0
	s_cmp_eq_u32 s28, 0
	s_cbranch_scc1 .LS5P_nstd1e
	global_store_dwordx4 v[240:241], v[232:235], off
	global_store_dwordx4 v[244:245], v[236:239], off
	v_lshl_add_u64 v[240:241], v[240:241], 0, s[50:51]
	v_lshl_add_u64 v[244:245], v[244:245], 0, s[50:51]
.LS5P_nstd1e:
	s_waitcnt vmcnt(6)
	v_cvt_pk_bf16_f32 v212, v102, v103
	v_cvt_pk_bf16_f32 v213, v104, v105
	v_cvt_pk_bf16_f32 v214, v98, v99
	v_cvt_pk_bf16_f32 v215, v100, v101
	v_fmac_f32_e32 v17, v154, v180
	v_fmac_f32_e32 v33, v154, v176
	v_fma_f32 v17, -v155, v176, v17
	v_fmac_f32_e32 v33, v155, v180
	v_mfma_f32_32x32x16_bf16 v[34:49], v[212:215], v[66:69], 0
	v_fmac_f32_e32 v16, v154, v17
	v_fmac_f32_e32 v32, v154, v33
	v_cvt_pk_bf16_f32 v184, v17, v33
	v_fma_f32 v16, -v155, v33, v16
	v_fmac_f32_e32 v32, v155, v17
	ds_write_b32 v207, v184 offset:4208
	v_fmac_f32_e32 v15, v154, v16
	v_fmac_f32_e32 v31, v154, v32
	v_cvt_pk_bf16_f32 v185, v16, v32
	v_fma_f32 v15, -v155, v32, v15
	v_fmac_f32_e32 v31, v155, v16
	ds_write_b32 v207, v185 offset:3936
	v_mfma_f32_32x32x16_bf16 v[50:65], v[212:215], v[74:77], 0
	v_fmac_f32_e32 v14, v154, v15
	v_fmac_f32_e32 v30, v154, v31
	v_cvt_pk_bf16_f32 v184, v15, v31
	v_fma_f32 v14, -v155, v31, v14
	v_fmac_f32_e32 v30, v155, v15
	ds_write_b32 v207, v184 offset:3664
	v_fmac_f32_e32 v13, v154, v14
	v_fmac_f32_e32 v29, v154, v30
	v_cvt_pk_bf16_f32 v185, v14, v30
	v_fma_f32 v13, -v155, v30, v13
	v_fmac_f32_e32 v29, v155, v14
	ds_write_b32 v207, v185 offset:3392
	v_fmac_f32_e32 v12, v154, v13
	v_fmac_f32_e32 v28, v154, v29
	v_cvt_pk_bf16_f32 v184, v13, v29
	v_fma_f32 v12, -v155, v29, v12
	v_fmac_f32_e32 v28, v155, v13
	ds_write_b32 v207, v184 offset:3120
	v_fmac_f32_e32 v11, v154, v12
	v_fmac_f32_e32 v27, v154, v28
	v_cvt_pk_bf16_f32 v185, v12, v28
	v_fma_f32 v11, -v155, v28, v11
	v_fmac_f32_e32 v27, v155, v12
	ds_write_b32 v207, v185 offset:2848
	v_fmac_f32_e32 v10, v154, v11
	v_fmac_f32_e32 v26, v154, v27
	v_cvt_pk_bf16_f32 v184, v11, v27
	v_fma_f32 v10, -v155, v27, v10
	v_fmac_f32_e32 v26, v155, v11
	ds_write_b32 v207, v184 offset:2576
	v_fmac_f32_e32 v9, v154, v10
	v_fmac_f32_e32 v25, v154, v26
	v_cvt_pk_bf16_f32 v185, v10, v26
	v_fma_f32 v9, -v155, v26, v9
	v_fmac_f32_e32 v25, v155, v10
	ds_write_b32 v207, v185 offset:2304
	v_fmac_f32_e32 v8, v154, v9
	v_fmac_f32_e32 v24, v154, v25
	v_cvt_pk_bf16_f32 v184, v9, v25
	v_fma_f32 v8, -v155, v25, v8
	v_fmac_f32_e32 v24, v155, v9
	ds_write_b32 v207, v184 offset:2032
	v_fmac_f32_e32 v7, v154, v8
	v_fmac_f32_e32 v23, v154, v24
	v_cvt_pk_bf16_f32 v185, v8, v24
	v_fma_f32 v7, -v155, v24, v7
	v_fmac_f32_e32 v23, v155, v8
	ds_write_b32 v207, v185 offset:1760
	v_fmac_f32_e32 v6, v154, v7
	v_fmac_f32_e32 v22, v154, v23
	v_cvt_pk_bf16_f32 v184, v7, v23
	v_fma_f32 v6, -v155, v23, v6
	v_fmac_f32_e32 v22, v155, v7
	ds_write_b32 v207, v184 offset:1488
	v_fmac_f32_e32 v5, v154, v6
	v_fmac_f32_e32 v21, v154, v22
	v_cvt_pk_bf16_f32 v185, v6, v22
	v_fma_f32 v5, -v155, v22, v5
	v_fmac_f32_e32 v21, v155, v6
	ds_write_b32 v207, v185 offset:1216
	v_fmac_f32_e32 v4, v154, v5
	v_fmac_f32_e32 v20, v154, v21
	v_cvt_pk_bf16_f32 v184, v5, v21
	v_fma_f32 v4, -v155, v21, v4
	v_fmac_f32_e32 v20, v155, v5
	ds_write_b32 v207, v184 offset:944
	v_fmac_f32_e32 v3, v154, v4
	v_fmac_f32_e32 v19, v154, v20
	v_cvt_pk_bf16_f32 v185, v4, v20
	v_fma_f32 v3, -v155, v20, v3
	v_fmac_f32_e32 v19, v155, v4
	ds_write_b32 v207, v185 offset:672
	v_fma_f32 v180, v154, v3, v2
	v_fma_f32 v176, v154, v19, v18
	v_cvt_pk_bf16_f32 v184, v3, v19
	v_fma_f32 v180, -v155, v19, v180
	v_fmac_f32_e32 v176, v155, v3
	ds_write_b32 v207, v184 offset:400
	v_cvt_pk_bf16_f32 v185, v180, v176
	ds_write_b32 v207, v185 offset:128
	s_add_u32 s28, s28, 1
	s_add_u32 s20, s28, 2
	s_cmp_lt_u32 s20, s52
	s_cselect_b64 s[58:59], s[50:51], 0
	v_lshl_add_u64 v[248:249], v[248:249], 0, s[58:59]
	global_load_dwordx4 v[98:101], v[248:249], off offset:16
	global_load_dwordx4 v[102:105], v[248:249], off
	ds_read_b128 v[216:219], v208
	ds_read_b128 v[220:223], v208 offset:4352
	ds_read_b128 v[224:227], v208 offset:64
	ds_read_b128 v[228:231], v208 offset:4416
	v_fmac_f32_e32 v49, v152, v182
	v_fmac_f32_e32 v65, v152, v178
	v_fma_f32 v49, -v153, v178, v49
	v_fmac_f32_e32 v65, v153, v182
	v_mfma_f32_32x32x16_bf16 v[2:17], v[212:215], v[70:73], 0
	v_fmac_f32_e32 v48, v152, v49
	v_fmac_f32_e32 v64, v152, v65
	v_cvt_pk_bf16_f32 v184, v49, v65
	v_fma_f32 v48, -v153, v65, v48
	v_fmac_f32_e32 v64, v153, v49
	ds_write_b32 v207, v184 offset:4080
	v_fmac_f32_e32 v47, v152, v48
	v_fmac_f32_e32 v63, v152, v64
	v_cvt_pk_bf16_f32 v185, v48, v64
	v_fma_f32 v47, -v153, v64, v47
	v_fmac_f32_e32 v63, v153, v48
	ds_write_b32 v207, v185 offset:3808
	v_mfma_f32_32x32x16_bf16 v[18:33], v[212:215], v[78:81], 0
	v_fmac_f32_e32 v46, v152, v47
	v_fmac_f32_e32 v62, v152, v63
	v_cvt_pk_bf16_f32 v184, v47, v63
	v_fma_f32 v46, -v153, v63, v46
	v_fmac_f32_e32 v62, v153, v47
	ds_write_b32 v207, v184 offset:3536
	v_fmac_f32_e32 v45, v152, v46
	v_fmac_f32_e32 v61, v152, v62
	v_cvt_pk_bf16_f32 v185, v46, v62
	v_fma_f32 v45, -v153, v62, v45
	v_fmac_f32_e32 v61, v153, v46
	ds_write_b32 v207, v185 offset:3264
	s_waitcnt lgkmcnt(6)
	v_mfma_f32_16x16x32_bf16 v[232:235], v[82:85], v[216:219], 0
	v_fmac_f32_e32 v44, v152, v45
	v_fmac_f32_e32 v60, v152, v61
	v_cvt_pk_bf16_f32 v184, v45, v61
	v_fma_f32 v44, -v153, v61, v44
	v_fmac_f32_e32 v60, v153, v45
	ds_write_b32 v207, v184 offset:2992
	v_mfma_f32_16x16x32_bf16 v[236:239], v[82:85], v[220:223], 0
	v_fmac_f32_e32 v43, v152, v44
	v_fmac_f32_e32 v59, v152, v60
	v_cvt_pk_bf16_f32 v185, v44, v60
	v_fma_f32 v43, -v153, v60, v43
	v_fmac_f32_e32 v59, v153, v44
	ds_write_b32 v207, v185 offset:2720
	s_waitcnt lgkmcnt(6)
	v_mfma_f32_16x16x32_bf16 v[232:235], v[86:89], v[224:227], v[232:235]
	v_fmac_f32_e32 v42, v152, v43
	v_fmac_f32_e32 v58, v152, v59
	v_cvt_pk_bf16_f32 v184, v43, v59
	v_fma_f32 v42, -v153, v59, v42
	v_fmac_f32_e32 v58, v153, v43
	ds_write_b32 v207, v184 offset:2448
	v_mfma_f32_16x16x32_bf16 v[236:239], v[86:89], v[228:231], v[236:239]
	v_fmac_f32_e32 v41, v152, v42
	v_fmac_f32_e32 v57, v152, v58
	v_cvt_pk_bf16_f32 v185, v42, v58
	v_fma_f32 v41, -v153, v58, v41
	v_fmac_f32_e32 v57, v153, v42
	ds_write_b32 v207, v185 offset:2176
	ds_read_b128 v[216:219], v208 offset:128
	ds_read_b128 v[220:223], v208 offset:4480
	ds_read_b128 v[224:227], v208 offset:192
	ds_read_b128 v[228:231], v208 offset:4544
	v_fmac_f32_e32 v40, v152, v41
	v_fmac_f32_e32 v56, v152, v57
	v_cvt_pk_bf16_f32 v184, v41, v57
	v_fma_f32 v40, -v153, v57, v40
	v_fmac_f32_e32 v56, v153, v41
	ds_write_b32 v207, v184 offset:1904
	v_fmac_f32_e32 v39, v152, v40
	v_fmac_f32_e32 v55, v152, v56
	v_cvt_pk_bf16_f32 v185, v40, v56
	v_fma_f32 v39, -v153, v56, v39
	v_fmac_f32_e32 v55, v153, v40
	ds_write_b32 v207, v185 offset:1632
	v_fmac_f32_e32 v38, v152, v39
	v_fmac_f32_e32 v54, v152, v55
	v_cvt_pk_bf16_f32 v184, v39, v55
	v_fma_f32 v38, -v153, v55, v38
	v_fmac_f32_e32 v54, v153, v39
	ds_write_b32 v207, v184 offset:1360
	s_waitcnt lgkmcnt(5)
	v_mfma_f32_16x16x32_bf16 v[232:235], v[90:93], v[216:219], v[232:235]
	v_fmac_f32_e32 v37, v152, v38
	v_fmac_f32_e32 v53, v152, v54
	v_cvt_pk_bf16_f32 v185, v38, v54
	v_fma_f32 v37, -v153, v54, v37
	v_fmac_f32_e32 v53, v153, v38
	ds_write_b32 v207, v185 offset:1088
	v_mfma_f32_16x16x32_bf16 v[236:239], v[90:93], v[220:223], v[236:239]
	v_fmac_f32_e32 v36, v152, v37
	v_fmac_f32_e32 v52, v152, v53
	v_cvt_pk_bf16_f32 v184, v37, v53
	v_fma_f32 v36, -v153, v53, v36
	v_fmac_f32_e32 v52, v153, v37
	ds_write_b32 v207, v184 offset:816
	s_waitcnt lgkmcnt(5)
	v_mfma_f32_16x16x32_bf16 v[232:235], v[94:97], v[224:227], v[232:235]
	v_fmac_f32_e32 v35, v152, v36
	v_fmac_f32_e32 v51, v152, v52
	v_cvt_pk_bf16_f32 v185, v36, v52
	v_fma_f32 v35, -v153, v52, v35
	v_fmac_f32_e32 v51, v153, v36
	ds_write_b32 v207, v185 offset:544
	v_mfma_f32_16x16x32_bf16 v[236:239], v[94:97], v[228:231], v[236:239]
	v_fma_f32 v182, v152, v35, v34
	v_fma_f32 v178, v152, v51, v50
	v_cvt_pk_bf16_f32 v184, v35, v51
	v_fma_f32 v182, -v153, v51, v182
	v_fmac_f32_e32 v178, v153, v35
	ds_write_b32 v207, v184 offset:272
	v_cvt_pk_bf16_f32 v185, v182, v178
	ds_write_b32 v207, v185 offset:0
	global_store_dwordx4 v[240:241], v[232:235], off
	global_store_dwordx4 v[244:245], v[236:239], off
	v_lshl_add_u64 v[240:241], v[240:241], 0, s[50:51]
	v_lshl_add_u64 v[244:245], v[244:245], 0, s[50:51]
	s_cmp_eq_u32 s28, 1
	s_cbranch_scc0 .LS5P_wd1o
	s_waitcnt vmcnt(4)
.LS5P_wd1o:
	s_waitcnt vmcnt(6)
	v_cvt_pk_bf16_f32 v212, v106, v107
	v_cvt_pk_bf16_f32 v213, v108, v109
	v_cvt_pk_bf16_f32 v214, v110, v111
	v_cvt_pk_bf16_f32 v215, v112, v113
	v_fmac_f32_e32 v17, v154, v180
	v_fmac_f32_e32 v33, v154, v176
	v_fma_f32 v17, -v155, v176, v17
	v_fmac_f32_e32 v33, v155, v180
	v_mfma_f32_32x32x16_bf16 v[34:49], v[212:215], v[66:69], 0
	v_fmac_f32_e32 v16, v154, v17
	v_fmac_f32_e32 v32, v154, v33
	v_cvt_pk_bf16_f32 v184, v17, v33
	v_fma_f32 v16, -v155, v33, v16
	v_fmac_f32_e32 v32, v155, v17
	ds_write_b32 v207, v184 offset:4208
	v_fmac_f32_e32 v15, v154, v16
	v_fmac_f32_e32 v31, v154, v32
	v_cvt_pk_bf16_f32 v185, v16, v32
	v_fma_f32 v15, -v155, v32, v15
	v_fmac_f32_e32 v31, v155, v16
	ds_write_b32 v207, v185 offset:3936
	v_mfma_f32_32x32x16_bf16 v[50:65], v[212:215], v[74:77], 0
	v_fmac_f32_e32 v14, v154, v15
	v_fmac_f32_e32 v30, v154, v31
	v_cvt_pk_bf16_f32 v184, v15, v31
	v_fma_f32 v14, -v155, v31, v14
	v_fmac_f32_e32 v30, v155, v15
	ds_write_b32 v207, v184 offset:3664
	v_fmac_f32_e32 v13, v154, v14
	v_fmac_f32_e32 v29, v154, v30
	v_cvt_pk_bf16_f32 v185, v14, v30
	v_fma_f32 v13, -v155, v30, v13
	v_fmac_f32_e32 v29, v155, v14
	ds_write_b32 v207, v185 offset:3392
	v_fmac_f32_e32 v12, v154, v13
	v_fmac_f32_e32 v28, v154, v29
	v_cvt_pk_bf16_f32 v184, v13, v29
	v_fma_f32 v12, -v155, v29, v12
	v_fmac_f32_e32 v28, v155, v13
	ds_write_b32 v207, v184 offset:3120
	v_fmac_f32_e32 v11, v154, v12
	v_fmac_f32_e32 v27, v154, v28
	v_cvt_pk_bf16_f32 v185, v12, v28
	v_fma_f32 v11, -v155, v28, v11
	v_fmac_f32_e32 v27, v155, v12
	ds_write_b32 v207, v185 offset:2848
	v_fmac_f32_e32 v10, v154, v11
	v_fmac_f32_e32 v26, v154, v27
	v_cvt_pk_bf16_f32 v184, v11, v27
	v_fma_f32 v10, -v155, v27, v10
	v_fmac_f32_e32 v26, v155, v11
	ds_write_b32 v207, v184 offset:2576
	v_fmac_f32_e32 v9, v154, v10
	v_fmac_f32_e32 v25, v154, v26
	v_cvt_pk_bf16_f32 v185, v10, v26
	v_fma_f32 v9, -v155, v26, v9
	v_fmac_f32_e32 v25, v155, v10
	ds_write_b32 v207, v185 offset:2304
	v_fmac_f32_e32 v8, v154, v9
	v_fmac_f32_e32 v24, v154, v25
	v_cvt_pk_bf16_f32 v184, v9, v25
	v_fma_f32 v8, -v155, v25, v8
	v_fmac_f32_e32 v24, v155, v9
	ds_write_b32 v207, v184 offset:2032
	v_fmac_f32_e32 v7, v154, v8
	v_fmac_f32_e32 v23, v154, v24
	v_cvt_pk_bf16_f32 v185, v8, v24
	v_fma_f32 v7, -v155, v24, v7
	v_fmac_f32_e32 v23, v155, v8
	ds_write_b32 v207, v185 offset:1760
	v_fmac_f32_e32 v6, v154, v7
	v_fmac_f32_e32 v22, v154, v23
	v_cvt_pk_bf16_f32 v184, v7, v23
	v_fma_f32 v6, -v155, v23, v6
	v_fmac_f32_e32 v22, v155, v7
	ds_write_b32 v207, v184 offset:1488
	v_fmac_f32_e32 v5, v154, v6
	v_fmac_f32_e32 v21, v154, v22
	v_cvt_pk_bf16_f32 v185, v6, v22
	v_fma_f32 v5, -v155, v22, v5
	v_fmac_f32_e32 v21, v155, v6
	ds_write_b32 v207, v185 offset:1216
	v_fmac_f32_e32 v4, v154, v5
	v_fmac_f32_e32 v20, v154, v21
	v_cvt_pk_bf16_f32 v184, v5, v21
	v_fma_f32 v4, -v155, v21, v4
	v_fmac_f32_e32 v20, v155, v5
	ds_write_b32 v207, v184 offset:944
	v_fmac_f32_e32 v3, v154, v4
	v_fmac_f32_e32 v19, v154, v20
	v_cvt_pk_bf16_f32 v185, v4, v20
	v_fma_f32 v3, -v155, v20, v3
	v_fmac_f32_e32 v19, v155, v4
	ds_write_b32 v207, v185 offset:672
	v_fma_f32 v180, v154, v3, v2
	v_fma_f32 v176, v154, v19, v18
	v_cvt_pk_bf16_f32 v184, v3, v19
	v_fma_f32 v180, -v155, v19, v180
	v_fmac_f32_e32 v176, v155, v3
	ds_write_b32 v207, v184 offset:400
	v_cvt_pk_bf16_f32 v185, v180, v176
	ds_write_b32 v207, v185 offset:128
	s_add_u32 s28, s28, 1
	s_cmp_lt_u32 s28, s52
	s_cbranch_scc1 .LS5P_loopd1
	s_branch .LS5P_epi
.LS5P_loopd0:
	s_add_u32 s20, s28, 2
	s_cmp_lt_u32 s20, s52
	s_cselect_b64 s[58:59], s[50:51], 0
	v_lshl_add_u64 v[248:249], v[248:249], 0, s[58:59]
	global_load_dwordx4 v[110:113], v[248:249], off offset:16
	global_load_dwordx4 v[106:109], v[248:249], off
	ds_read_b128 v[216:219], v208
	ds_read_b128 v[220:223], v208 offset:4352
	ds_read_b128 v[224:227], v208 offset:64
	ds_read_b128 v[228:231], v208 offset:4416
	v_fmac_f32_e32 v34, v152, v182
	v_fmac_f32_e32 v50, v152, v178
	v_fma_f32 v34, -v153, v178, v34
	v_fmac_f32_e32 v50, v153, v182
	v_mfma_f32_32x32x16_bf16 v[2:17], v[212:215], v[70:73], 0
	v_fmac_f32_e32 v35, v152, v34
	v_fmac_f32_e32 v51, v152, v50
	v_cvt_pk_bf16_f32 v184, v34, v50
	v_fma_f32 v35, -v153, v50, v35
	v_fmac_f32_e32 v51, v153, v34
	ds_write_b32 v207, v184 offset:0
	v_fmac_f32_e32 v36, v152, v35
	v_fmac_f32_e32 v52, v152, v51
	v_cvt_pk_bf16_f32 v185, v35, v51
	v_fma_f32 v36, -v153, v51, v36
	v_fmac_f32_e32 v52, v153, v35
	ds_write_b32 v207, v185 offset:272
	v_mfma_f32_32x32x16_bf16 v[18:33], v[212:215], v[78:81], 0
	v_fmac_f32_e32 v37, v152, v36
	v_fmac_f32_e32 v53, v152, v52
	v_cvt_pk_bf16_f32 v184, v36, v52
	v_fma_f32 v37, -v153, v52, v37
	v_fmac_f32_e32 v53, v153, v36
	ds_write_b32 v207, v184 offset:544
	v_fmac_f32_e32 v38, v152, v37
	v_fmac_f32_e32 v54, v152, v53
	v_cvt_pk_bf16_f32 v185, v37, v53
	v_fma_f32 v38, -v153, v53, v38
	v_fmac_f32_e32 v54, v153, v37
	ds_write_b32 v207, v185 offset:816
	s_waitcnt lgkmcnt(6)
	v_mfma_f32_16x16x32_bf16 v[232:235], v[82:85], v[216:219], 0
	v_fmac_f32_e32 v39, v152, v38
	v_fmac_f32_e32 v55, v152, v54
	v_cvt_pk_bf16_f32 v184, v38, v54
	v_fma_f32 v39, -v153, v54, v39
	v_fmac_f32_e32 v55, v153, v38
	ds_write_b32 v207, v184 offset:1088
	v_mfma_f32_16x16x32_bf16 v[236:239], v[82:85], v[220:223], 0
	v_fmac_f32_e32 v40, v152, v39
	v_fmac_f32_e32 v56, v152, v55
	v_cvt_pk_bf16_f32 v185, v39, v55
	v_fma_f32 v40, -v153, v55, v40
	v_fmac_f32_e32 v56, v153, v39
	ds_write_b32 v207, v185 offset:1360
	s_waitcnt lgkmcnt(6)
	v_mfma_f32_16x16x32_bf16 v[232:235], v[86:89], v[224:227], v[232:235]
	v_fmac_f32_e32 v41, v152, v40
	v_fmac_f32_e32 v57, v152, v56
	v_cvt_pk_bf16_f32 v184, v40, v56
	v_fma_f32 v41, -v153, v56, v41
	v_fmac_f32_e32 v57, v153, v40
	ds_write_b32 v207, v184 offset:1632
	v_mfma_f32_16x16x32_bf16 v[236:239], v[86:89], v[228:231], v[236:239]
	v_fmac_f32_e32 v42, v152, v41
	v_fmac_f32_e32 v58, v152, v57
	v_cvt_pk_bf16_f32 v185, v41, v57
	v_fma_f32 v42, -v153, v57, v42
	v_fmac_f32_e32 v58, v153, v41
	ds_write_b32 v207, v185 offset:1904
	ds_read_b128 v[216:219], v208 offset:128
	ds_read_b128 v[220:223], v208 offset:4480
	ds_read_b128 v[224:227], v208 offset:192
	ds_read_b128 v[228:231], v208 offset:4544
	v_fmac_f32_e32 v43, v152, v42
	v_fmac_f32_e32 v59, v152, v58
	v_cvt_pk_bf16_f32 v184, v42, v58
	v_fma_f32 v43, -v153, v58, v43
	v_fmac_f32_e32 v59, v153, v42
	ds_write_b32 v207, v184 offset:2176
	v_fmac_f32_e32 v44, v152, v43
	v_fmac_f32_e32 v60, v152, v59
	v_cvt_pk_bf16_f32 v185, v43, v59
	v_fma_f32 v44, -v153, v59, v44
	v_fmac_f32_e32 v60, v153, v43
	ds_write_b32 v207, v185 offset:2448
	v_fmac_f32_e32 v45, v152, v44
	v_fmac_f32_e32 v61, v152, v60
	v_cvt_pk_bf16_f32 v184, v44, v60
	v_fma_f32 v45, -v153, v60, v45
	v_fmac_f32_e32 v61, v153, v44
	ds_write_b32 v207, v184 offset:2720
	s_waitcnt lgkmcnt(5)
	v_mfma_f32_16x16x32_bf16 v[232:235], v[90:93], v[216:219], v[232:235]
	v_fmac_f32_e32 v46, v152, v45
	v_fmac_f32_e32 v62, v152, v61
	v_cvt_pk_bf16_f32 v185, v45, v61
	v_fma_f32 v46, -v153, v61, v46
	v_fmac_f32_e32 v62, v153, v45
	ds_write_b32 v207, v185 offset:2992
	v_mfma_f32_16x16x32_bf16 v[236:239], v[90:93], v[220:223], v[236:239]
	v_fmac_f32_e32 v47, v152, v46
	v_fmac_f32_e32 v63, v152, v62
	v_cvt_pk_bf16_f32 v184, v46, v62
	v_fma_f32 v47, -v153, v62, v47
	v_fmac_f32_e32 v63, v153, v46
	ds_write_b32 v207, v184 offset:3264
	s_waitcnt lgkmcnt(5)
	v_mfma_f32_16x16x32_bf16 v[232:235], v[94:97], v[224:227], v[232:235]
	v_fmac_f32_e32 v48, v152, v47
	v_fmac_f32_e32 v64, v152, v63
	v_cvt_pk_bf16_f32 v185, v47, v63
	v_fma_f32 v48, -v153, v63, v48
	v_fmac_f32_e32 v64, v153, v47
	ds_write_b32 v207, v185 offset:3536
	v_mfma_f32_16x16x32_bf16 v[236:239], v[94:97], v[228:231], v[236:239]
	v_fma_f32 v182, v152, v48, v49
	v_fma_f32 v178, v152, v64, v65
	v_cvt_pk_bf16_f32 v184, v48, v64
	v_fma_f32 v182, -v153, v64, v182
	v_fmac_f32_e32 v178, v153, v48
	ds_write_b32 v207, v184 offset:3808
	v_cvt_pk_bf16_f32 v185, v182, v178
	ds_write_b32 v207, v185 offset:4080
	s_cmp_eq_u32 s28, 0
	s_cbranch_scc1 .LS5P_nstd0e
	global_store_dwordx4 v[240:241], v[232:235], off
	global_store_dwordx4 v[244:245], v[236:239], off
	v_lshl_add_u64 v[240:241], v[240:241], 0, s[50:51]
	v_lshl_add_u64 v[244:245], v[244:245], 0, s[50:51]
.LS5P_nstd0e:
	s_waitcnt vmcnt(6)
	v_cvt_pk_bf16_f32 v212, v102, v103
	v_cvt_pk_bf16_f32 v213, v104, v105
	v_cvt_pk_bf16_f32 v214, v98, v99
	v_cvt_pk_bf16_f32 v215, v100, v101
	v_fmac_f32_e32 v2, v154, v180
	v_fmac_f32_e32 v18, v154, v176
	v_fma_f32 v2, -v155, v176, v2
	v_fmac_f32_e32 v18, v155, v180
	v_mfma_f32_32x32x16_bf16 v[34:49], v[212:215], v[66:69], 0
	v_fmac_f32_e32 v3, v154, v2
	v_fmac_f32_e32 v19, v154, v18
	v_cvt_pk_bf16_f32 v184, v2, v18
	v_fma_f32 v3, -v155, v18, v3
	v_fmac_f32_e32 v19, v155, v2
	ds_write_b32 v207, v184 offset:128
	v_fmac_f32_e32 v4, v154, v3
	v_fmac_f32_e32 v20, v154, v19
	v_cvt_pk_bf16_f32 v185, v3, v19
	v_fma_f32 v4, -v155, v19, v4
	v_fmac_f32_e32 v20, v155, v3
	ds_write_b32 v207, v185 offset:400
	v_mfma_f32_32x32x16_bf16 v[50:65], v[212:215], v[74:77], 0
	v_fmac_f32_e32 v5, v154, v4
	v_fmac_f32_e32 v21, v154, v20
	v_cvt_pk_bf16_f32 v184, v4, v20
	v_fma_f32 v5, -v155, v20, v5
	v_fmac_f32_e32 v21, v155, v4
	ds_write_b32 v207, v184 offset:672
	v_fmac_f32_e32 v6, v154, v5
	v_fmac_f32_e32 v22, v154, v21
	v_cvt_pk_bf16_f32 v185, v5, v21
	v_fma_f32 v6, -v155, v21, v6
	v_fmac_f32_e32 v22, v155, v5
	ds_write_b32 v207, v185 offset:944
	v_fmac_f32_e32 v7, v154, v6
	v_fmac_f32_e32 v23, v154, v22
	v_cvt_pk_bf16_f32 v184, v6, v22
	v_fma_f32 v7, -v155, v22, v7
	v_fmac_f32_e32 v23, v155, v6
	ds_write_b32 v207, v184 offset:1216
	v_fmac_f32_e32 v8, v154, v7
	v_fmac_f32_e32 v24, v154, v23
	v_cvt_pk_bf16_f32 v185, v7, v23
	v_fma_f32 v8, -v155, v23, v8
	v_fmac_f32_e32 v24, v155, v7
	ds_write_b32 v207, v185 offset:1488
	v_fmac_f32_e32 v9, v154, v8
	v_fmac_f32_e32 v25, v154, v24
	v_cvt_pk_bf16_f32 v184, v8, v24
	v_fma_f32 v9, -v155, v24, v9
	v_fmac_f32_e32 v25, v155, v8
	ds_write_b32 v207, v184 offset:1760
	v_fmac_f32_e32 v10, v154, v9
	v_fmac_f32_e32 v26, v154, v25
	v_cvt_pk_bf16_f32 v185, v9, v25
	v_fma_f32 v10, -v155, v25, v10
	v_fmac_f32_e32 v26, v155, v9
	ds_write_b32 v207, v185 offset:2032
	v_fmac_f32_e32 v11, v154, v10
	v_fmac_f32_e32 v27, v154, v26
	v_cvt_pk_bf16_f32 v184, v10, v26
	v_fma_f32 v11, -v155, v26, v11
	v_fmac_f32_e32 v27, v155, v10
	ds_write_b32 v207, v184 offset:2304
	v_fmac_f32_e32 v12, v154, v11
	v_fmac_f32_e32 v28, v154, v27
	v_cvt_pk_bf16_f32 v185, v11, v27
	v_fma_f32 v12, -v155, v27, v12
	v_fmac_f32_e32 v28, v155, v11
	ds_write_b32 v207, v185 offset:2576
	v_fmac_f32_e32 v13, v154, v12
	v_fmac_f32_e32 v29, v154, v28
	v_cvt_pk_bf16_f32 v184, v12, v28
	v_fma_f32 v13, -v155, v28, v13
	v_fmac_f32_e32 v29, v155, v12
	ds_write_b32 v207, v184 offset:2848
	v_fmac_f32_e32 v14, v154, v13
	v_fmac_f32_e32 v30, v154, v29
	v_cvt_pk_bf16_f32 v185, v13, v29
	v_fma_f32 v14, -v155, v29, v14
	v_fmac_f32_e32 v30, v155, v13
	ds_write_b32 v207, v185 offset:3120
	v_fmac_f32_e32 v15, v154, v14
	v_fmac_f32_e32 v31, v154, v30
	v_cvt_pk_bf16_f32 v184, v14, v30
	v_fma_f32 v15, -v155, v30, v15
	v_fmac_f32_e32 v31, v155, v14
	ds_write_b32 v207, v184 offset:3392
	v_fmac_f32_e32 v16, v154, v15
	v_fmac_f32_e32 v32, v154, v31
	v_cvt_pk_bf16_f32 v185, v15, v31
	v_fma_f32 v16, -v155, v31, v16
	v_fmac_f32_e32 v32, v155, v15
	ds_write_b32 v207, v185 offset:3664
	v_fma_f32 v180, v154, v16, v17
	v_fma_f32 v176, v154, v32, v33
	v_cvt_pk_bf16_f32 v184, v16, v32
	v_fma_f32 v180, -v155, v32, v180
	v_fmac_f32_e32 v176, v155, v16
	ds_write_b32 v207, v184 offset:3936
	v_cvt_pk_bf16_f32 v185, v180, v176
	ds_write_b32 v207, v185 offset:4208
	s_add_u32 s28, s28, 1
	s_add_u32 s20, s28, 2
	s_cmp_lt_u32 s20, s52
	s_cselect_b64 s[58:59], s[50:51], 0
	v_lshl_add_u64 v[248:249], v[248:249], 0, s[58:59]
	global_load_dwordx4 v[98:101], v[248:249], off offset:16
	global_load_dwordx4 v[102:105], v[248:249], off
	ds_read_b128 v[216:219], v208
	ds_read_b128 v[220:223], v208 offset:4352
	ds_read_b128 v[224:227], v208 offset:64
	ds_read_b128 v[228:231], v208 offset:4416
	v_fmac_f32_e32 v34, v152, v182
	v_fmac_f32_e32 v50, v152, v178
	v_fma_f32 v34, -v153, v178, v34
	v_fmac_f32_e32 v50, v153, v182
	v_mfma_f32_32x32x16_bf16 v[2:17], v[212:215], v[70:73], 0
	v_fmac_f32_e32 v35, v152, v34
	v_fmac_f32_e32 v51, v152, v50
	v_cvt_pk_bf16_f32 v184, v34, v50
	v_fma_f32 v35, -v153, v50, v35
	v_fmac_f32_e32 v51, v153, v34
	ds_write_b32 v207, v184 offset:0
	v_fmac_f32_e32 v36, v152, v35
	v_fmac_f32_e32 v52, v152, v51
	v_cvt_pk_bf16_f32 v185, v35, v51
	v_fma_f32 v36, -v153, v51, v36
	v_fmac_f32_e32 v52, v153, v35
	ds_write_b32 v207, v185 offset:272
	v_mfma_f32_32x32x16_bf16 v[18:33], v[212:215], v[78:81], 0
	v_fmac_f32_e32 v37, v152, v36
	v_fmac_f32_e32 v53, v152, v52
	v_cvt_pk_bf16_f32 v184, v36, v52
	v_fma_f32 v37, -v153, v52, v37
	v_fmac_f32_e32 v53, v153, v36
	ds_write_b32 v207, v184 offset:544
	v_fmac_f32_e32 v38, v152, v37
	v_fmac_f32_e32 v54, v152, v53
	v_cvt_pk_bf16_f32 v185, v37, v53
	v_fma_f32 v38, -v153, v53, v38
	v_fmac_f32_e32 v54, v153, v37
	ds_write_b32 v207, v185 offset:816
	s_waitcnt lgkmcnt(6)
	v_mfma_f32_16x16x32_bf16 v[232:235], v[82:85], v[216:219], 0
	v_fmac_f32_e32 v39, v152, v38
	v_fmac_f32_e32 v55, v152, v54
	v_cvt_pk_bf16_f32 v184, v38, v54
	v_fma_f32 v39, -v153, v54, v39
	v_fmac_f32_e32 v55, v153, v38
	ds_write_b32 v207, v184 offset:1088
	v_mfma_f32_16x16x32_bf16 v[236:239], v[82:85], v[220:223], 0
	v_fmac_f32_e32 v40, v152, v39
	v_fmac_f32_e32 v56, v152, v55
	v_cvt_pk_bf16_f32 v185, v39, v55
	v_fma_f32 v40, -v153, v55, v40
	v_fmac_f32_e32 v56, v153, v39
	ds_write_b32 v207, v185 offset:1360
	s_waitcnt lgkmcnt(6)
	v_mfma_f32_16x16x32_bf16 v[232:235], v[86:89], v[224:227], v[232:235]
	v_fmac_f32_e32 v41, v152, v40
	v_fmac_f32_e32 v57, v152, v56
	v_cvt_pk_bf16_f32 v184, v40, v56
	v_fma_f32 v41, -v153, v56, v41
	v_fmac_f32_e32 v57, v153, v40
	ds_write_b32 v207, v184 offset:1632
	v_mfma_f32_16x16x32_bf16 v[236:239], v[86:89], v[228:231], v[236:239]
	v_fmac_f32_e32 v42, v152, v41
	v_fmac_f32_e32 v58, v152, v57
	v_cvt_pk_bf16_f32 v185, v41, v57
	v_fma_f32 v42, -v153, v57, v42
	v_fmac_f32_e32 v58, v153, v41
	ds_write_b32 v207, v185 offset:1904
	ds_read_b128 v[216:219], v208 offset:128
	ds_read_b128 v[220:223], v208 offset:4480
	ds_read_b128 v[224:227], v208 offset:192
	ds_read_b128 v[228:231], v208 offset:4544
	v_fmac_f32_e32 v43, v152, v42
	v_fmac_f32_e32 v59, v152, v58
	v_cvt_pk_bf16_f32 v184, v42, v58
	v_fma_f32 v43, -v153, v58, v43
	v_fmac_f32_e32 v59, v153, v42
	ds_write_b32 v207, v184 offset:2176
	v_fmac_f32_e32 v44, v152, v43
	v_fmac_f32_e32 v60, v152, v59
	v_cvt_pk_bf16_f32 v185, v43, v59
	v_fma_f32 v44, -v153, v59, v44
	v_fmac_f32_e32 v60, v153, v43
	ds_write_b32 v207, v185 offset:2448
	v_fmac_f32_e32 v45, v152, v44
	v_fmac_f32_e32 v61, v152, v60
	v_cvt_pk_bf16_f32 v184, v44, v60
	v_fma_f32 v45, -v153, v60, v45
	v_fmac_f32_e32 v61, v153, v44
	ds_write_b32 v207, v184 offset:2720
	s_waitcnt lgkmcnt(5)
	v_mfma_f32_16x16x32_bf16 v[232:235], v[90:93], v[216:219], v[232:235]
	v_fmac_f32_e32 v46, v152, v45
	v_fmac_f32_e32 v62, v152, v61
	v_cvt_pk_bf16_f32 v185, v45, v61
	v_fma_f32 v46, -v153, v61, v46
	v_fmac_f32_e32 v62, v153, v45
	ds_write_b32 v207, v185 offset:2992
	v_mfma_f32_16x16x32_bf16 v[236:239], v[90:93], v[220:223], v[236:239]
	v_fmac_f32_e32 v47, v152, v46
	v_fmac_f32_e32 v63, v152, v62
	v_cvt_pk_bf16_f32 v184, v46, v62
	v_fma_f32 v47, -v153, v62, v47
	v_fmac_f32_e32 v63, v153, v46
	ds_write_b32 v207, v184 offset:3264
	s_waitcnt lgkmcnt(5)
	v_mfma_f32_16x16x32_bf16 v[232:235], v[94:97], v[224:227], v[232:235]
	v_fmac_f32_e32 v48, v152, v47
	v_fmac_f32_e32 v64, v152, v63
	v_cvt_pk_bf16_f32 v185, v47, v63
	v_fma_f32 v48, -v153, v63, v48
	v_fmac_f32_e32 v64, v153, v47
	ds_write_b32 v207, v185 offset:3536
	v_mfma_f32_16x16x32_bf16 v[236:239], v[94:97], v[228:231], v[236:239]
	v_fma_f32 v182, v152, v48, v49
	v_fma_f32 v178, v152, v64, v65
	v_cvt_pk_bf16_f32 v184, v48, v64
	v_fma_f32 v182, -v153, v64, v182
	v_fmac_f32_e32 v178, v153, v48
	ds_write_b32 v207, v184 offset:3808
	v_cvt_pk_bf16_f32 v185, v182, v178
	ds_write_b32 v207, v185 offset:4080
	global_store_dwordx4 v[240:241], v[232:235], off
	global_store_dwordx4 v[244:245], v[236:239], off
	v_lshl_add_u64 v[240:241], v[240:241], 0, s[50:51]
	v_lshl_add_u64 v[244:245], v[244:245], 0, s[50:51]
	s_cmp_eq_u32 s28, 1
	s_cbranch_scc0 .LS5P_wd0o
	s_waitcnt vmcnt(4)
.LS5P_wd0o:
	s_waitcnt vmcnt(6)
	v_cvt_pk_bf16_f32 v212, v106, v107
	v_cvt_pk_bf16_f32 v213, v108, v109
	v_cvt_pk_bf16_f32 v214, v110, v111
	v_cvt_pk_bf16_f32 v215, v112, v113
	v_fmac_f32_e32 v2, v154, v180
	v_fmac_f32_e32 v18, v154, v176
	v_fma_f32 v2, -v155, v176, v2
	v_fmac_f32_e32 v18, v155, v180
	v_mfma_f32_32x32x16_bf16 v[34:49], v[212:215], v[66:69], 0
	v_fmac_f32_e32 v3, v154, v2
	v_fmac_f32_e32 v19, v154, v18
	v_cvt_pk_bf16_f32 v184, v2, v18
	v_fma_f32 v3, -v155, v18, v3
	v_fmac_f32_e32 v19, v155, v2
	ds_write_b32 v207, v184 offset:128
	v_fmac_f32_e32 v4, v154, v3
	v_fmac_f32_e32 v20, v154, v19
	v_cvt_pk_bf16_f32 v185, v3, v19
	v_fma_f32 v4, -v155, v19, v4
	v_fmac_f32_e32 v20, v155, v3
	ds_write_b32 v207, v185 offset:400
	v_mfma_f32_32x32x16_bf16 v[50:65], v[212:215], v[74:77], 0
	v_fmac_f32_e32 v5, v154, v4
	v_fmac_f32_e32 v21, v154, v20
	v_cvt_pk_bf16_f32 v184, v4, v20
	v_fma_f32 v5, -v155, v20, v5
	v_fmac_f32_e32 v21, v155, v4
	ds_write_b32 v207, v184 offset:672
	v_fmac_f32_e32 v6, v154, v5
	v_fmac_f32_e32 v22, v154, v21
	v_cvt_pk_bf16_f32 v185, v5, v21
	v_fma_f32 v6, -v155, v21, v6
	v_fmac_f32_e32 v22, v155, v5
	ds_write_b32 v207, v185 offset:944
	v_fmac_f32_e32 v7, v154, v6
	v_fmac_f32_e32 v23, v154, v22
	v_cvt_pk_bf16_f32 v184, v6, v22
	v_fma_f32 v7, -v155, v22, v7
	v_fmac_f32_e32 v23, v155, v6
	ds_write_b32 v207, v184 offset:1216
	v_fmac_f32_e32 v8, v154, v7
	v_fmac_f32_e32 v24, v154, v23
	v_cvt_pk_bf16_f32 v185, v7, v23
	v_fma_f32 v8, -v155, v23, v8
	v_fmac_f32_e32 v24, v155, v7
	ds_write_b32 v207, v185 offset:1488
	v_fmac_f32_e32 v9, v154, v8
	v_fmac_f32_e32 v25, v154, v24
	v_cvt_pk_bf16_f32 v184, v8, v24
	v_fma_f32 v9, -v155, v24, v9
	v_fmac_f32_e32 v25, v155, v8
	ds_write_b32 v207, v184 offset:1760
	v_fmac_f32_e32 v10, v154, v9
	v_fmac_f32_e32 v26, v154, v25
	v_cvt_pk_bf16_f32 v185, v9, v25
	v_fma_f32 v10, -v155, v25, v10
	v_fmac_f32_e32 v26, v155, v9
	ds_write_b32 v207, v185 offset:2032
	v_fmac_f32_e32 v11, v154, v10
	v_fmac_f32_e32 v27, v154, v26
	v_cvt_pk_bf16_f32 v184, v10, v26
	v_fma_f32 v11, -v155, v26, v11
	v_fmac_f32_e32 v27, v155, v10
	ds_write_b32 v207, v184 offset:2304
	v_fmac_f32_e32 v12, v154, v11
	v_fmac_f32_e32 v28, v154, v27
	v_cvt_pk_bf16_f32 v185, v11, v27
	v_fma_f32 v12, -v155, v27, v12
	v_fmac_f32_e32 v28, v155, v11
	ds_write_b32 v207, v185 offset:2576
	v_fmac_f32_e32 v13, v154, v12
	v_fmac_f32_e32 v29, v154, v28
	v_cvt_pk_bf16_f32 v184, v12, v28
	v_fma_f32 v13, -v155, v28, v13
	v_fmac_f32_e32 v29, v155, v12
	ds_write_b32 v207, v184 offset:2848
	v_fmac_f32_e32 v14, v154, v13
	v_fmac_f32_e32 v30, v154, v29
	v_cvt_pk_bf16_f32 v185, v13, v29
	v_fma_f32 v14, -v155, v29, v14
	v_fmac_f32_e32 v30, v155, v13
	ds_write_b32 v207, v185 offset:3120
	v_fmac_f32_e32 v15, v154, v14
	v_fmac_f32_e32 v31, v154, v30
	v_cvt_pk_bf16_f32 v184, v14, v30
	v_fma_f32 v15, -v155, v30, v15
	v_fmac_f32_e32 v31, v155, v14
	ds_write_b32 v207, v184 offset:3392
	v_fmac_f32_e32 v16, v154, v15
	v_fmac_f32_e32 v32, v154, v31
	v_cvt_pk_bf16_f32 v185, v15, v31
	v_fma_f32 v16, -v155, v31, v16
	v_fmac_f32_e32 v32, v155, v15
	ds_write_b32 v207, v185 offset:3664
	v_fma_f32 v180, v154, v16, v17
	v_fma_f32 v176, v154, v32, v33
	v_cvt_pk_bf16_f32 v184, v16, v32
	v_fma_f32 v180, -v155, v32, v180
	v_fmac_f32_e32 v176, v155, v16
	ds_write_b32 v207, v184 offset:3936
	v_cvt_pk_bf16_f32 v185, v180, v176
	ds_write_b32 v207, v185 offset:4208
	s_add_u32 s28, s28, 1
	s_cmp_lt_u32 s28, s52
	s_cbranch_scc1 .LS5P_loopd0
.LS5P_epi:
	ds_read_b128 v[216:219], v208
	ds_read_b128 v[220:223], v208 offset:4352
	ds_read_b128 v[224:227], v208 offset:64
	ds_read_b128 v[228:231], v208 offset:4416
	ds_read_b128 v[2:5], v208 offset:128
	ds_read_b128 v[6:9], v208 offset:4480
	ds_read_b128 v[10:13], v208 offset:192
	ds_read_b128 v[14:17], v208 offset:4544
	s_waitcnt lgkmcnt(6)
	v_mfma_f32_16x16x32_bf16 v[232:235], v[82:85], v[216:219], 0
	v_mfma_f32_16x16x32_bf16 v[236:239], v[82:85], v[220:223], 0
	s_waitcnt lgkmcnt(4)
	v_mfma_f32_16x16x32_bf16 v[232:235], v[86:89], v[224:227], v[232:235]
	v_mfma_f32_16x16x32_bf16 v[236:239], v[86:89], v[228:231], v[236:239]
	s_waitcnt lgkmcnt(2)
	v_mfma_f32_16x16x32_bf16 v[232:235], v[90:93], v[2:5], v[232:235]
	v_mfma_f32_16x16x32_bf16 v[236:239], v[90:93], v[6:9], v[236:239]
	s_waitcnt lgkmcnt(0)
	v_mfma_f32_16x16x32_bf16 v[232:235], v[94:97], v[10:13], v[232:235]
	v_mfma_f32_16x16x32_bf16 v[236:239], v[94:97], v[14:17], v[236:239]
	s_nop 7
	global_store_dwordx4 v[240:241], v[232:235], off
	global_store_dwordx4 v[244:245], v[236:239], off
